# P8b final rmsnorm: gain loads hoisted out of the row loop, all row loads of a wave issued up front with counted vmcnt
# baseline (speedup 1.0000x reference)
; #define GAS __attribute__((address_space(1)))
; __device__ __forceinline__ const float* kin(int k) { KArgs p = (KArgs)__builtin_amdgcn_kernarg_segment_ptr(); asm volatile("" : "+s"(p)); return p->in[k]; }
; __device__ __forceinline__ void rms_row2_f32(float* xrow0, const float* g, int lane, bool second_valid) {
;     const int hl = lane & 31, hw = lane >> 5;
;     if (hw && !second_valid) return;
;     GAS f32x4* xr = (GAS f32x4*)(xrow0 + (size_t)hw * DM) + hl; const GAS f32x4* gr = (const GAS f32x4*)g + hl;
;     f32x4 v[8]; float s = 0.f;
; #pragma unroll
;     for (int j = 0; j < 8; ++j) { v[j] = NTL(xr + 32 * j); s += (v[j].x * v[j].x + v[j].y * v[j].y) + (v[j].z * v[j].z + v[j].w * v[j].w); }
; __global__ void __launch_bounds__(NWAVES * 64, 2) mk_fwd(Args args) {
;     ...
;     { const float* gg_ = kin(20); for (int m = 2 * GW_; m < T; m += 2 * NGW) rms_row2_f32(out + (size_t)m * DM, gg_, F.lane, m + 1 < T); }
.LBB0_1991:
	s_lshl_b32 s2, s33, 4
	s_lshl_b32 s3, s50, 1
	s_add_i32 s2, s3, s2
	s_cmpk_gt_i32 s2, 0x43ff
	s_cbranch_scc1 .LBB0_1994
	v_mbcnt_lo_u32_b32 v3, -1, 0
	v_mbcnt_hi_u32_b32 v3, -1, v3
	v_and_b32_e32 v4, 64, v3
	v_add_u32_e32 v4, 64, v4
	v_xor_b32_e32 v5, 1, v3
	v_cmp_lt_i32_e32 vcc, v5, v4
	s_load_dwordx2 s[0:1], s[0:1], 0xa0
	v_and_b32_e32 v2, 31, v189
	v_cndmask_b32_e32 v5, v3, v5, vcc
	s_waitcnt vmcnt(4)
	v_lshlrev_b32_e32 v12, 2, v5
	v_xor_b32_e32 v5, 2, v3
	v_cmp_lt_i32_e32 vcc, v5, v4
	v_mov_b32_e32 v1, 0
	v_lshlrev_b32_e32 v0, 7, v189
	v_cndmask_b32_e32 v5, v3, v5, vcc
	v_lshlrev_b32_e32 v13, 2, v5
	v_xor_b32_e32 v5, 4, v3
	v_cmp_lt_i32_e32 vcc, v5, v4
	v_lshlrev_b32_e32 v2, 4, v2
	s_ashr_i32 s3, s2, 31
	v_cndmask_b32_e32 v5, v3, v5, vcc
	v_lshlrev_b32_e32 v14, 2, v5
	v_xor_b32_e32 v5, 8, v3
	v_cmp_lt_i32_e32 vcc, v5, v4
	v_and_b32_e32 v0, 0x1000, v0
	s_lshl_b32 s4, s18, 4
	v_cndmask_b32_e32 v5, v3, v5, vcc
	v_lshlrev_b32_e32 v15, 2, v5
	v_xor_b32_e32 v5, 16, v3
	v_cmp_lt_i32_e32 vcc, v5, v4
	s_ashr_i32 s5, s4, 31
	s_lshl_b64 s[6:7], s[4:5], 12
	v_cndmask_b32_e32 v3, v3, v5, vcc
	v_lshlrev_b32_e32 v16, 2, v3
	v_mov_b32_e32 v3, v1
	s_waitcnt lgkmcnt(0)
	v_lshl_add_u64 v[8:9], s[0:1], 0, v[2:3]
	s_lshl_b64 s[0:1], s[2:3], 12
	v_lshl_add_u64 v[0:1], v[0:1], 0, s[0:1]
	v_or_b32_e32 v0, v0, v2
	v_lshl_add_u64 v[10:11], s[20:21], 0, v[0:1]
	v_mov_b32_e32 v17, 0x358637bd
	s_mov_b32 s3, 0xf800000
	v_mov_b32_e32 v18, 0x260
	global_load_dwordx4 v[20:23], v[8:9], off offset:0
	global_load_dwordx4 v[24:27], v[8:9], off offset:512
	global_load_dwordx4 v[28:31], v[8:9], off offset:1024
	global_load_dwordx4 v[32:35], v[8:9], off offset:1536
	global_load_dwordx4 v[36:39], v[8:9], off offset:2048
	global_load_dwordx4 v[40:43], v[8:9], off offset:2560
	global_load_dwordx4 v[44:47], v[8:9], off offset:3072
	global_load_dwordx4 v[48:51], v[8:9], off offset:3584
.Lp8b_outer:
	v_mov_b32_e32 v2, v10
	v_mov_b32_e32 v3, v11
	s_mov_b32 s8, 0
	global_load_dwordx4 v[52:55], v[10:11], off offset:0
	global_load_dwordx4 v[56:59], v[10:11], off offset:512
	global_load_dwordx4 v[60:63], v[10:11], off offset:1024
	global_load_dwordx4 v[64:67], v[10:11], off offset:1536
	global_load_dwordx4 v[68:71], v[10:11], off offset:2048
	global_load_dwordx4 v[72:75], v[10:11], off offset:2560
	global_load_dwordx4 v[76:79], v[10:11], off offset:3072
	global_load_dwordx4 v[80:83], v[10:11], off offset:3584
	v_lshl_add_u64 v[10:11], v[10:11], 0, s[6:7]
	s_add_i32 s2, s2, s4
	s_add_i32 s8, s8, 1
	s_cmpk_lt_i32 s2, 0x4400
	s_cbranch_scc0 .Lp8b_issued
	global_load_dwordx4 v[84:87], v[10:11], off offset:0
	global_load_dwordx4 v[88:91], v[10:11], off offset:512
	global_load_dwordx4 v[92:95], v[10:11], off offset:1024
	global_load_dwordx4 v[96:99], v[10:11], off offset:1536
	global_load_dwordx4 v[100:103], v[10:11], off offset:2048
	global_load_dwordx4 v[104:107], v[10:11], off offset:2560
	global_load_dwordx4 v[108:111], v[10:11], off offset:3072
	global_load_dwordx4 v[112:115], v[10:11], off offset:3584
	v_lshl_add_u64 v[10:11], v[10:11], 0, s[6:7]
	s_add_i32 s2, s2, s4
	s_add_i32 s8, s8, 1
	s_cmpk_lt_i32 s2, 0x4400
	s_cbranch_scc0 .Lp8b_issued
	global_load_dwordx4 v[116:119], v[10:11], off offset:0
	global_load_dwordx4 v[120:123], v[10:11], off offset:512
	global_load_dwordx4 v[124:127], v[10:11], off offset:1024
	global_load_dwordx4 v[128:131], v[10:11], off offset:1536
	global_load_dwordx4 v[132:135], v[10:11], off offset:2048
	global_load_dwordx4 v[136:139], v[10:11], off offset:2560
	global_load_dwordx4 v[140:143], v[10:11], off offset:3072
	global_load_dwordx4 v[144:147], v[10:11], off offset:3584
	v_lshl_add_u64 v[10:11], v[10:11], 0, s[6:7]
	s_add_i32 s2, s2, s4
	s_add_i32 s8, s8, 1
	s_cmpk_lt_i32 s2, 0x4400
	s_cbranch_scc0 .Lp8b_issued
	global_load_dwordx4 v[148:151], v[10:11], off offset:0
	global_load_dwordx4 v[152:155], v[10:11], off offset:512
	global_load_dwordx4 v[156:159], v[10:11], off offset:1024
	global_load_dwordx4 v[160:163], v[10:11], off offset:1536
	global_load_dwordx4 v[164:167], v[10:11], off offset:2048
	global_load_dwordx4 v[168:171], v[10:11], off offset:2560
	global_load_dwordx4 v[172:175], v[10:11], off offset:3072
	global_load_dwordx4 v[176:179], v[10:11], off offset:3584
	v_lshl_add_u64 v[10:11], v[10:11], 0, s[6:7]
	s_add_i32 s2, s2, s4
	s_add_i32 s8, s8, 1
	s_cmpk_lt_i32 s2, 0x4400
	s_cbranch_scc0 .Lp8b_issued
	global_load_dwordx4 v[180:183], v[10:11], off offset:0
	global_load_dwordx4 v[184:187], v[10:11], off offset:512
	global_load_dwordx4 v[188:191], v[10:11], off offset:1024
	global_load_dwordx4 v[192:195], v[10:11], off offset:1536
	global_load_dwordx4 v[196:199], v[10:11], off offset:2048
	global_load_dwordx4 v[200:203], v[10:11], off offset:2560
	global_load_dwordx4 v[204:207], v[10:11], off offset:3072
	global_load_dwordx4 v[208:211], v[10:11], off offset:3584
	v_lshl_add_u64 v[10:11], v[10:11], 0, s[6:7]
	s_add_i32 s2, s2, s4
	s_add_i32 s8, s8, 1
.Lp8b_issued:
	s_cmp_lt_u32 s8, 4
	s_cbranch_scc0 .Lp8b_go
	s_waitcnt vmcnt(0)
; __device__ __forceinline__ void rms_row2_f32(float* xrow0, const float* g, int lane, bool second_valid) {
;     ...
;     for (int j = 0; j < 8; ++j) { v[j] = NTL(xr + 32 * j); s += (v[j].x * v[j].x + v[j].y * v[j].y) + (v[j].z * v[j].z + v[j].w * v[j].w); }
; #pragma unroll
;     for (int o = 1; o < 32; o <<= 1) s += __shfl_xor(s, o);
;     const float rstd = 1.f / sqrtf(s * (1.f / DM) + EPS);
; #pragma unroll
;     for (int j = 0; j < 8; ++j) { const f32x4 gg = gr[32 * j]; xr[32 * j] = v[j] * rstd * gg; }
.Lp8b_go:
	s_waitcnt vmcnt(24)
	v_mov_b32_e32 v214, v53
	v_mov_b32_e32 v215, v57
	v_mov_b32_e32 v218, v55
	v_mov_b32_e32 v219, v59
	v_mov_b32_e32 v212, v52
	v_mov_b32_e32 v213, v56
	v_mov_b32_e32 v216, v54
	v_mov_b32_e32 v217, v58
	v_pk_mul_f32 v[220:221], v[62:63], v[62:63]
	v_pk_mul_f32 v[222:223], v[60:61], v[60:61]
	v_pk_mul_f32 v[214:215], v[214:215], v[214:215]
	v_pk_mul_f32 v[218:219], v[218:219], v[218:219]
	v_pk_mov_b32 v[236:237], v[222:223], v[220:221] op_sel:[1,0]
	v_mov_b32_e32 v223, v221
	v_pk_fma_f32 v[212:213], v[212:213], v[212:213], v[214:215]
	v_pk_fma_f32 v[214:215], v[216:217], v[216:217], v[218:219]
	v_mul_f32_e32 v224, v65, v65
	v_mul_f32_e32 v226, v67, v67
	v_pk_add_f32 v[216:217], v[236:237], v[222:223]
	v_pk_add_f32 v[212:213], v[212:213], v[214:215]
	v_mul_f32_e32 v4, v68, v68
	v_mul_f32_e32 v235, v69, v69
	v_mul_f32_e32 v238, v70, v70
	v_mul_f32_e32 v239, v71, v71
	v_pk_fma_f32 v[220:221], v[64:65], v[64:65], v[224:225] op_sel_hi:[1,1,0]
	v_pk_fma_f32 v[224:225], v[66:67], v[66:67], v[226:227] op_sel_hi:[1,1,0]
	v_pk_add_f32 v[214:215], v[216:217], v[216:217] op_sel:[0,1] op_sel_hi:[1,0]
	v_pk_add_f32 v[212:213], v[212:213], v[212:213] op_sel:[0,1] op_sel_hi:[1,0]
	v_pk_mul_f32 v[228:229], v[74:75], v[74:75]
	v_pk_mul_f32 v[230:231], v[72:73], v[72:73]
	v_mov_b32_e32 v221, v238
	v_mov_b32_e32 v225, v239
	v_mov_b32_e32 v215, v235
	v_mov_b32_e32 v213, v4
	v_pk_mov_b32 v[226:227], v[230:231], v[228:229] op_sel:[1,0]
	v_mov_b32_e32 v231, v229
	v_pk_add_f32 v[216:217], v[220:221], v[224:225]
	v_pk_add_f32 v[212:213], v[212:213], v[214:215]
	v_mul_f32_e32 v232, v77, v77
	v_mul_f32_e32 v234, v79, v79
	v_pk_add_f32 v[218:219], v[226:227], v[230:231]
	v_pk_add_f32 v[212:213], v[212:213], v[216:217]
	v_mul_f32_e32 v240, v80, v80
	v_mul_f32_e32 v241, v81, v81
	v_mul_f32_e32 v242, v82, v82
	v_mul_f32_e32 v243, v83, v83
	v_pk_fma_f32 v[228:229], v[76:77], v[76:77], v[232:233] op_sel_hi:[1,1,0]
	v_pk_fma_f32 v[232:233], v[78:79], v[78:79], v[234:235] op_sel_hi:[1,1,0]
	v_pk_add_f32 v[218:219], v[218:219], v[218:219] op_sel:[0,1] op_sel_hi:[1,0]
	v_pk_add_f32 v[212:213], v[212:213], v[212:213] op_sel:[0,1] op_sel_hi:[1,0]
	v_mov_b32_e32 v229, v242
	v_mov_b32_e32 v233, v243
	v_mov_b32_e32 v219, v241
	v_mov_b32_e32 v213, v240
	v_pk_add_f32 v[220:221], v[228:229], v[232:233]
	v_pk_add_f32 v[212:213], v[212:213], v[218:219]
	s_nop 0
	v_pk_add_f32 v[212:213], v[212:213], v[220:221]
	s_nop 0
	v_add_f32_e32 v4, v212, v213
	ds_bpermute_b32 v212, v12, v4
	s_waitcnt lgkmcnt(0)
	v_add_f32_e32 v4, v4, v212
	ds_bpermute_b32 v212, v13, v4
	s_waitcnt lgkmcnt(0)
	v_add_f32_e32 v4, v4, v212
	ds_bpermute_b32 v212, v14, v4
	s_waitcnt lgkmcnt(0)
	v_add_f32_e32 v4, v4, v212
	ds_bpermute_b32 v212, v15, v4
	s_waitcnt lgkmcnt(0)
	v_add_f32_e32 v4, v4, v212
	ds_bpermute_b32 v212, v16, v4
	s_waitcnt lgkmcnt(0)
	v_add_f32_e32 v4, v4, v212
	v_fmamk_f32 v4, v4, 0x3a800000, v17
	v_mul_f32_e32 v212, 0x4f800000, v4
	v_cmp_gt_f32_e32 vcc, s3, v4
	s_nop 1
	v_cndmask_b32_e32 v4, v4, v212, vcc
	v_sqrt_f32_e32 v212, v4
	s_nop 0
	v_add_u32_e32 v213, -1, v212
	v_add_u32_e32 v214, 1, v212
	v_fma_f32 v215, -v213, v212, v4
	v_fma_f32 v216, -v214, v212, v4
	v_cmp_ge_f32_e64 s[0:1], 0, v215
	s_nop 1
	v_cndmask_b32_e64 v212, v212, v213, s[0:1]
	v_cmp_lt_f32_e64 s[0:1], 0, v216
	s_nop 1
	v_cndmask_b32_e64 v212, v212, v214, s[0:1]
	v_mul_f32_e32 v213, 0x37800000, v212
	v_cndmask_b32_e32 v212, v212, v213, vcc
	v_cmp_class_f32_e32 vcc, v4, v18
	s_nop 1
	v_cndmask_b32_e32 v4, v212, v4, vcc
	v_div_scale_f32 v212, s[0:1], v4, v4, 1.0
	v_rcp_f32_e32 v213, v212
	v_div_scale_f32 v214, vcc, 1.0, v4, 1.0
	v_fma_f32 v215, -v212, v213, 1.0
	v_fmac_f32_e32 v213, v215, v213
	v_mul_f32_e32 v215, v214, v213
	v_fma_f32 v216, -v212, v215, v214
	v_fmac_f32_e32 v215, v216, v213
	v_fma_f32 v212, -v212, v215, v214
	v_div_fmas_f32 v212, v212, v213, v215
	v_div_fixup_f32 v212, v212, v4, 1.0
	v_pk_mul_f32 v[52:53], v[52:53], v[212:213] op_sel_hi:[1,0]
	v_pk_mul_f32 v[54:55], v[54:55], v[212:213] op_sel_hi:[1,0]
	v_pk_mul_f32 v[52:53], v[20:21], v[52:53]
	v_pk_mul_f32 v[54:55], v[22:23], v[54:55]
	global_store_dwordx4 v[2:3], v[52:55], off offset:0
	v_pk_mul_f32 v[56:57], v[56:57], v[212:213] op_sel_hi:[1,0]
	v_pk_mul_f32 v[58:59], v[58:59], v[212:213] op_sel_hi:[1,0]
	v_pk_mul_f32 v[56:57], v[24:25], v[56:57]
	v_pk_mul_f32 v[58:59], v[26:27], v[58:59]
	global_store_dwordx4 v[2:3], v[56:59], off offset:512
	v_pk_mul_f32 v[60:61], v[60:61], v[212:213] op_sel_hi:[1,0]
	v_pk_mul_f32 v[62:63], v[62:63], v[212:213] op_sel_hi:[1,0]
	v_pk_mul_f32 v[60:61], v[28:29], v[60:61]
	v_pk_mul_f32 v[62:63], v[30:31], v[62:63]
	global_store_dwordx4 v[2:3], v[60:63], off offset:1024
	v_pk_mul_f32 v[64:65], v[64:65], v[212:213] op_sel_hi:[1,0]
	v_pk_mul_f32 v[66:67], v[66:67], v[212:213] op_sel_hi:[1,0]
	v_pk_mul_f32 v[64:65], v[32:33], v[64:65]
	v_pk_mul_f32 v[66:67], v[34:35], v[66:67]
	global_store_dwordx4 v[2:3], v[64:67], off offset:1536
	v_pk_mul_f32 v[68:69], v[68:69], v[212:213] op_sel_hi:[1,0]
	v_pk_mul_f32 v[70:71], v[70:71], v[212:213] op_sel_hi:[1,0]
	v_pk_mul_f32 v[68:69], v[36:37], v[68:69]
	v_pk_mul_f32 v[70:71], v[38:39], v[70:71]
	global_store_dwordx4 v[2:3], v[68:71], off offset:2048
	v_pk_mul_f32 v[72:73], v[72:73], v[212:213] op_sel_hi:[1,0]
	v_pk_mul_f32 v[74:75], v[74:75], v[212:213] op_sel_hi:[1,0]
	v_pk_mul_f32 v[72:73], v[40:41], v[72:73]
	v_pk_mul_f32 v[74:75], v[42:43], v[74:75]
	global_store_dwordx4 v[2:3], v[72:75], off offset:2560
	v_pk_mul_f32 v[76:77], v[76:77], v[212:213] op_sel_hi:[1,0]
	v_pk_mul_f32 v[78:79], v[78:79], v[212:213] op_sel_hi:[1,0]
	v_pk_mul_f32 v[76:77], v[44:45], v[76:77]
	v_pk_mul_f32 v[78:79], v[46:47], v[78:79]
	global_store_dwordx4 v[2:3], v[76:79], off offset:3072
	v_pk_mul_f32 v[80:81], v[80:81], v[212:213] op_sel_hi:[1,0]
	v_pk_mul_f32 v[82:83], v[82:83], v[212:213] op_sel_hi:[1,0]
	v_pk_mul_f32 v[80:81], v[48:49], v[80:81]
	v_pk_mul_f32 v[82:83], v[50:51], v[82:83]
	global_store_dwordx4 v[2:3], v[80:83], off offset:3584
	v_lshl_add_u64 v[2:3], v[2:3], 0, s[6:7]
	s_cmp_lt_u32 1, s8
	s_cbranch_scc0 .Lp8b_done
; __device__ __forceinline__ void rms_row2_f32(float* xrow0, const float* g, int lane, bool second_valid) {
;     ...
;     for (int j = 0; j < 8; ++j) { v[j] = NTL(xr + 32 * j); s += (v[j].x * v[j].x + v[j].y * v[j].y) + (v[j].z * v[j].z + v[j].w * v[j].w); }
; #pragma unroll
;     for (int o = 1; o < 32; o <<= 1) s += __shfl_xor(s, o);
;     const float rstd = 1.f / sqrtf(s * (1.f / DM) + EPS);
; #pragma unroll
;     for (int j = 0; j < 8; ++j) { const f32x4 gg = gr[32 * j]; xr[32 * j] = v[j] * rstd * gg; }
	s_waitcnt vmcnt(24)
	v_mov_b32_e32 v214, v85
	v_mov_b32_e32 v215, v89
	v_mov_b32_e32 v218, v87
	v_mov_b32_e32 v219, v91
	v_mov_b32_e32 v212, v84
	v_mov_b32_e32 v213, v88
	v_mov_b32_e32 v216, v86
	v_mov_b32_e32 v217, v90
	v_pk_mul_f32 v[220:221], v[94:95], v[94:95]
	v_pk_mul_f32 v[222:223], v[92:93], v[92:93]
	v_pk_mul_f32 v[214:215], v[214:215], v[214:215]
	v_pk_mul_f32 v[218:219], v[218:219], v[218:219]
	v_pk_mov_b32 v[236:237], v[222:223], v[220:221] op_sel:[1,0]
	v_mov_b32_e32 v223, v221
	v_pk_fma_f32 v[212:213], v[212:213], v[212:213], v[214:215]
	v_pk_fma_f32 v[214:215], v[216:217], v[216:217], v[218:219]
	v_mul_f32_e32 v224, v97, v97
	v_mul_f32_e32 v226, v99, v99
	v_pk_add_f32 v[216:217], v[236:237], v[222:223]
	v_pk_add_f32 v[212:213], v[212:213], v[214:215]
	v_mul_f32_e32 v4, v100, v100
	v_mul_f32_e32 v235, v101, v101
	v_mul_f32_e32 v238, v102, v102
	v_mul_f32_e32 v239, v103, v103
	v_pk_fma_f32 v[220:221], v[96:97], v[96:97], v[224:225] op_sel_hi:[1,1,0]
	v_pk_fma_f32 v[224:225], v[98:99], v[98:99], v[226:227] op_sel_hi:[1,1,0]
	v_pk_add_f32 v[214:215], v[216:217], v[216:217] op_sel:[0,1] op_sel_hi:[1,0]
	v_pk_add_f32 v[212:213], v[212:213], v[212:213] op_sel:[0,1] op_sel_hi:[1,0]
	v_pk_mul_f32 v[228:229], v[106:107], v[106:107]
	v_pk_mul_f32 v[230:231], v[104:105], v[104:105]
	v_mov_b32_e32 v221, v238
	v_mov_b32_e32 v225, v239
	v_mov_b32_e32 v215, v235
	v_mov_b32_e32 v213, v4
	v_pk_mov_b32 v[226:227], v[230:231], v[228:229] op_sel:[1,0]
	v_mov_b32_e32 v231, v229
	v_pk_add_f32 v[216:217], v[220:221], v[224:225]
	v_pk_add_f32 v[212:213], v[212:213], v[214:215]
	v_mul_f32_e32 v232, v109, v109
	v_mul_f32_e32 v234, v111, v111
	v_pk_add_f32 v[218:219], v[226:227], v[230:231]
	v_pk_add_f32 v[212:213], v[212:213], v[216:217]
	v_mul_f32_e32 v240, v112, v112
	v_mul_f32_e32 v241, v113, v113
	v_mul_f32_e32 v242, v114, v114
	v_mul_f32_e32 v243, v115, v115
	v_pk_fma_f32 v[228:229], v[108:109], v[108:109], v[232:233] op_sel_hi:[1,1,0]
	v_pk_fma_f32 v[232:233], v[110:111], v[110:111], v[234:235] op_sel_hi:[1,1,0]
	v_pk_add_f32 v[218:219], v[218:219], v[218:219] op_sel:[0,1] op_sel_hi:[1,0]
	v_pk_add_f32 v[212:213], v[212:213], v[212:213] op_sel:[0,1] op_sel_hi:[1,0]
	v_mov_b32_e32 v229, v242
	v_mov_b32_e32 v233, v243
	v_mov_b32_e32 v219, v241
	v_mov_b32_e32 v213, v240
	v_pk_add_f32 v[220:221], v[228:229], v[232:233]
	v_pk_add_f32 v[212:213], v[212:213], v[218:219]
	s_nop 0
	v_pk_add_f32 v[212:213], v[212:213], v[220:221]
	s_nop 0
	v_add_f32_e32 v4, v212, v213
	ds_bpermute_b32 v212, v12, v4
	s_waitcnt lgkmcnt(0)
	v_add_f32_e32 v4, v4, v212
	ds_bpermute_b32 v212, v13, v4
	s_waitcnt lgkmcnt(0)
	v_add_f32_e32 v4, v4, v212
	ds_bpermute_b32 v212, v14, v4
	s_waitcnt lgkmcnt(0)
	v_add_f32_e32 v4, v4, v212
	ds_bpermute_b32 v212, v15, v4
	s_waitcnt lgkmcnt(0)
	v_add_f32_e32 v4, v4, v212
	ds_bpermute_b32 v212, v16, v4
	s_waitcnt lgkmcnt(0)
	v_add_f32_e32 v4, v4, v212
	v_fmamk_f32 v4, v4, 0x3a800000, v17
	v_mul_f32_e32 v212, 0x4f800000, v4
	v_cmp_gt_f32_e32 vcc, s3, v4
	s_nop 1
	v_cndmask_b32_e32 v4, v4, v212, vcc
	v_sqrt_f32_e32 v212, v4
	s_nop 0
	v_add_u32_e32 v213, -1, v212
	v_add_u32_e32 v214, 1, v212
	v_fma_f32 v215, -v213, v212, v4
	v_fma_f32 v216, -v214, v212, v4
	v_cmp_ge_f32_e64 s[0:1], 0, v215
	s_nop 1
	v_cndmask_b32_e64 v212, v212, v213, s[0:1]
	v_cmp_lt_f32_e64 s[0:1], 0, v216
	s_nop 1
	v_cndmask_b32_e64 v212, v212, v214, s[0:1]
	v_mul_f32_e32 v213, 0x37800000, v212
	v_cndmask_b32_e32 v212, v212, v213, vcc
	v_cmp_class_f32_e32 vcc, v4, v18
	s_nop 1
	v_cndmask_b32_e32 v4, v212, v4, vcc
	v_div_scale_f32 v212, s[0:1], v4, v4, 1.0
	v_rcp_f32_e32 v213, v212
	v_div_scale_f32 v214, vcc, 1.0, v4, 1.0
	v_fma_f32 v215, -v212, v213, 1.0
	v_fmac_f32_e32 v213, v215, v213
	v_mul_f32_e32 v215, v214, v213
	v_fma_f32 v216, -v212, v215, v214
	v_fmac_f32_e32 v215, v216, v213
	v_fma_f32 v212, -v212, v215, v214
	v_div_fmas_f32 v212, v212, v213, v215
	v_div_fixup_f32 v212, v212, v4, 1.0
	v_pk_mul_f32 v[84:85], v[84:85], v[212:213] op_sel_hi:[1,0]
	v_pk_mul_f32 v[86:87], v[86:87], v[212:213] op_sel_hi:[1,0]
	v_pk_mul_f32 v[84:85], v[20:21], v[84:85]
	v_pk_mul_f32 v[86:87], v[22:23], v[86:87]
	global_store_dwordx4 v[2:3], v[84:87], off offset:0
	v_pk_mul_f32 v[88:89], v[88:89], v[212:213] op_sel_hi:[1,0]
	v_pk_mul_f32 v[90:91], v[90:91], v[212:213] op_sel_hi:[1,0]
	v_pk_mul_f32 v[88:89], v[24:25], v[88:89]
	v_pk_mul_f32 v[90:91], v[26:27], v[90:91]
	global_store_dwordx4 v[2:3], v[88:91], off offset:512
	v_pk_mul_f32 v[92:93], v[92:93], v[212:213] op_sel_hi:[1,0]
	v_pk_mul_f32 v[94:95], v[94:95], v[212:213] op_sel_hi:[1,0]
	v_pk_mul_f32 v[92:93], v[28:29], v[92:93]
	v_pk_mul_f32 v[94:95], v[30:31], v[94:95]
	global_store_dwordx4 v[2:3], v[92:95], off offset:1024
	v_pk_mul_f32 v[96:97], v[96:97], v[212:213] op_sel_hi:[1,0]
	v_pk_mul_f32 v[98:99], v[98:99], v[212:213] op_sel_hi:[1,0]
	v_pk_mul_f32 v[96:97], v[32:33], v[96:97]
	v_pk_mul_f32 v[98:99], v[34:35], v[98:99]
	global_store_dwordx4 v[2:3], v[96:99], off offset:1536
	v_pk_mul_f32 v[100:101], v[100:101], v[212:213] op_sel_hi:[1,0]
	v_pk_mul_f32 v[102:103], v[102:103], v[212:213] op_sel_hi:[1,0]
	v_pk_mul_f32 v[100:101], v[36:37], v[100:101]
	v_pk_mul_f32 v[102:103], v[38:39], v[102:103]
	global_store_dwordx4 v[2:3], v[100:103], off offset:2048
	v_pk_mul_f32 v[104:105], v[104:105], v[212:213] op_sel_hi:[1,0]
	v_pk_mul_f32 v[106:107], v[106:107], v[212:213] op_sel_hi:[1,0]
	v_pk_mul_f32 v[104:105], v[40:41], v[104:105]
	v_pk_mul_f32 v[106:107], v[42:43], v[106:107]
	global_store_dwordx4 v[2:3], v[104:107], off offset:2560
	v_pk_mul_f32 v[108:109], v[108:109], v[212:213] op_sel_hi:[1,0]
	v_pk_mul_f32 v[110:111], v[110:111], v[212:213] op_sel_hi:[1,0]
	v_pk_mul_f32 v[108:109], v[44:45], v[108:109]
	v_pk_mul_f32 v[110:111], v[46:47], v[110:111]
	global_store_dwordx4 v[2:3], v[108:111], off offset:3072
	v_pk_mul_f32 v[112:113], v[112:113], v[212:213] op_sel_hi:[1,0]
	v_pk_mul_f32 v[114:115], v[114:115], v[212:213] op_sel_hi:[1,0]
	v_pk_mul_f32 v[112:113], v[48:49], v[112:113]
	v_pk_mul_f32 v[114:115], v[50:51], v[114:115]
	global_store_dwordx4 v[2:3], v[112:115], off offset:3584
	v_lshl_add_u64 v[2:3], v[2:3], 0, s[6:7]
	s_cmp_lt_u32 2, s8
	s_cbranch_scc0 .Lp8b_done
; __device__ __forceinline__ void rms_row2_f32(float* xrow0, const float* g, int lane, bool second_valid) {
;     ...
;     for (int j = 0; j < 8; ++j) { v[j] = NTL(xr + 32 * j); s += (v[j].x * v[j].x + v[j].y * v[j].y) + (v[j].z * v[j].z + v[j].w * v[j].w); }
; #pragma unroll
;     for (int o = 1; o < 32; o <<= 1) s += __shfl_xor(s, o);
;     const float rstd = 1.f / sqrtf(s * (1.f / DM) + EPS);
; #pragma unroll
;     for (int j = 0; j < 8; ++j) { const f32x4 gg = gr[32 * j]; xr[32 * j] = v[j] * rstd * gg; }
	s_waitcnt vmcnt(24)
	v_mov_b32_e32 v214, v117
	v_mov_b32_e32 v215, v121
	v_mov_b32_e32 v218, v119
	v_mov_b32_e32 v219, v123
	v_mov_b32_e32 v212, v116
	v_mov_b32_e32 v213, v120
	v_mov_b32_e32 v216, v118
	v_mov_b32_e32 v217, v122
	v_pk_mul_f32 v[220:221], v[126:127], v[126:127]
	v_pk_mul_f32 v[222:223], v[124:125], v[124:125]
	v_pk_mul_f32 v[214:215], v[214:215], v[214:215]
	v_pk_mul_f32 v[218:219], v[218:219], v[218:219]
	v_pk_mov_b32 v[236:237], v[222:223], v[220:221] op_sel:[1,0]
	v_mov_b32_e32 v223, v221
	v_pk_fma_f32 v[212:213], v[212:213], v[212:213], v[214:215]
	v_pk_fma_f32 v[214:215], v[216:217], v[216:217], v[218:219]
	v_mul_f32_e32 v224, v129, v129
	v_mul_f32_e32 v226, v131, v131
	v_pk_add_f32 v[216:217], v[236:237], v[222:223]
	v_pk_add_f32 v[212:213], v[212:213], v[214:215]
	v_mul_f32_e32 v4, v132, v132
	v_mul_f32_e32 v235, v133, v133
	v_mul_f32_e32 v238, v134, v134
	v_mul_f32_e32 v239, v135, v135
	v_pk_fma_f32 v[220:221], v[128:129], v[128:129], v[224:225] op_sel_hi:[1,1,0]
	v_pk_fma_f32 v[224:225], v[130:131], v[130:131], v[226:227] op_sel_hi:[1,1,0]
	v_pk_add_f32 v[214:215], v[216:217], v[216:217] op_sel:[0,1] op_sel_hi:[1,0]
	v_pk_add_f32 v[212:213], v[212:213], v[212:213] op_sel:[0,1] op_sel_hi:[1,0]
	v_pk_mul_f32 v[228:229], v[138:139], v[138:139]
	v_pk_mul_f32 v[230:231], v[136:137], v[136:137]
	v_mov_b32_e32 v221, v238
	v_mov_b32_e32 v225, v239
	v_mov_b32_e32 v215, v235
	v_mov_b32_e32 v213, v4
	v_pk_mov_b32 v[226:227], v[230:231], v[228:229] op_sel:[1,0]
	v_mov_b32_e32 v231, v229
	v_pk_add_f32 v[216:217], v[220:221], v[224:225]
	v_pk_add_f32 v[212:213], v[212:213], v[214:215]
	v_mul_f32_e32 v232, v141, v141
	v_mul_f32_e32 v234, v143, v143
	v_pk_add_f32 v[218:219], v[226:227], v[230:231]
	v_pk_add_f32 v[212:213], v[212:213], v[216:217]
	v_mul_f32_e32 v240, v144, v144
	v_mul_f32_e32 v241, v145, v145
	v_mul_f32_e32 v242, v146, v146
	v_mul_f32_e32 v243, v147, v147
	v_pk_fma_f32 v[228:229], v[140:141], v[140:141], v[232:233] op_sel_hi:[1,1,0]
	v_pk_fma_f32 v[232:233], v[142:143], v[142:143], v[234:235] op_sel_hi:[1,1,0]
	v_pk_add_f32 v[218:219], v[218:219], v[218:219] op_sel:[0,1] op_sel_hi:[1,0]
	v_pk_add_f32 v[212:213], v[212:213], v[212:213] op_sel:[0,1] op_sel_hi:[1,0]
	v_mov_b32_e32 v229, v242
	v_mov_b32_e32 v233, v243
	v_mov_b32_e32 v219, v241
	v_mov_b32_e32 v213, v240
	v_pk_add_f32 v[220:221], v[228:229], v[232:233]
	v_pk_add_f32 v[212:213], v[212:213], v[218:219]
	s_nop 0
	v_pk_add_f32 v[212:213], v[212:213], v[220:221]
	s_nop 0
	v_add_f32_e32 v4, v212, v213
	ds_bpermute_b32 v212, v12, v4
	s_waitcnt lgkmcnt(0)
	v_add_f32_e32 v4, v4, v212
	ds_bpermute_b32 v212, v13, v4
	s_waitcnt lgkmcnt(0)
	v_add_f32_e32 v4, v4, v212
	ds_bpermute_b32 v212, v14, v4
	s_waitcnt lgkmcnt(0)
	v_add_f32_e32 v4, v4, v212
	ds_bpermute_b32 v212, v15, v4
	s_waitcnt lgkmcnt(0)
	v_add_f32_e32 v4, v4, v212
	ds_bpermute_b32 v212, v16, v4
	s_waitcnt lgkmcnt(0)
	v_add_f32_e32 v4, v4, v212
	v_fmamk_f32 v4, v4, 0x3a800000, v17
	v_mul_f32_e32 v212, 0x4f800000, v4
	v_cmp_gt_f32_e32 vcc, s3, v4
	s_nop 1
	v_cndmask_b32_e32 v4, v4, v212, vcc
	v_sqrt_f32_e32 v212, v4
	s_nop 0
	v_add_u32_e32 v213, -1, v212
	v_add_u32_e32 v214, 1, v212
	v_fma_f32 v215, -v213, v212, v4
	v_fma_f32 v216, -v214, v212, v4
	v_cmp_ge_f32_e64 s[0:1], 0, v215
	s_nop 1
	v_cndmask_b32_e64 v212, v212, v213, s[0:1]
	v_cmp_lt_f32_e64 s[0:1], 0, v216
	s_nop 1
	v_cndmask_b32_e64 v212, v212, v214, s[0:1]
	v_mul_f32_e32 v213, 0x37800000, v212
	v_cndmask_b32_e32 v212, v212, v213, vcc
	v_cmp_class_f32_e32 vcc, v4, v18
	s_nop 1
	v_cndmask_b32_e32 v4, v212, v4, vcc
	v_div_scale_f32 v212, s[0:1], v4, v4, 1.0
	v_rcp_f32_e32 v213, v212
	v_div_scale_f32 v214, vcc, 1.0, v4, 1.0
	v_fma_f32 v215, -v212, v213, 1.0
	v_fmac_f32_e32 v213, v215, v213
	v_mul_f32_e32 v215, v214, v213
	v_fma_f32 v216, -v212, v215, v214
	v_fmac_f32_e32 v215, v216, v213
	v_fma_f32 v212, -v212, v215, v214
	v_div_fmas_f32 v212, v212, v213, v215
	v_div_fixup_f32 v212, v212, v4, 1.0
	v_pk_mul_f32 v[116:117], v[116:117], v[212:213] op_sel_hi:[1,0]
	v_pk_mul_f32 v[118:119], v[118:119], v[212:213] op_sel_hi:[1,0]
	v_pk_mul_f32 v[116:117], v[20:21], v[116:117]
	v_pk_mul_f32 v[118:119], v[22:23], v[118:119]
	global_store_dwordx4 v[2:3], v[116:119], off offset:0
	v_pk_mul_f32 v[120:121], v[120:121], v[212:213] op_sel_hi:[1,0]
	v_pk_mul_f32 v[122:123], v[122:123], v[212:213] op_sel_hi:[1,0]
	v_pk_mul_f32 v[120:121], v[24:25], v[120:121]
	v_pk_mul_f32 v[122:123], v[26:27], v[122:123]
	global_store_dwordx4 v[2:3], v[120:123], off offset:512
	v_pk_mul_f32 v[124:125], v[124:125], v[212:213] op_sel_hi:[1,0]
	v_pk_mul_f32 v[126:127], v[126:127], v[212:213] op_sel_hi:[1,0]
	v_pk_mul_f32 v[124:125], v[28:29], v[124:125]
	v_pk_mul_f32 v[126:127], v[30:31], v[126:127]
	global_store_dwordx4 v[2:3], v[124:127], off offset:1024
	v_pk_mul_f32 v[128:129], v[128:129], v[212:213] op_sel_hi:[1,0]
	v_pk_mul_f32 v[130:131], v[130:131], v[212:213] op_sel_hi:[1,0]
	v_pk_mul_f32 v[128:129], v[32:33], v[128:129]
	v_pk_mul_f32 v[130:131], v[34:35], v[130:131]
	global_store_dwordx4 v[2:3], v[128:131], off offset:1536
	v_pk_mul_f32 v[132:133], v[132:133], v[212:213] op_sel_hi:[1,0]
	v_pk_mul_f32 v[134:135], v[134:135], v[212:213] op_sel_hi:[1,0]
	v_pk_mul_f32 v[132:133], v[36:37], v[132:133]
	v_pk_mul_f32 v[134:135], v[38:39], v[134:135]
	global_store_dwordx4 v[2:3], v[132:135], off offset:2048
	v_pk_mul_f32 v[136:137], v[136:137], v[212:213] op_sel_hi:[1,0]
	v_pk_mul_f32 v[138:139], v[138:139], v[212:213] op_sel_hi:[1,0]
	v_pk_mul_f32 v[136:137], v[40:41], v[136:137]
	v_pk_mul_f32 v[138:139], v[42:43], v[138:139]
	global_store_dwordx4 v[2:3], v[136:139], off offset:2560
	v_pk_mul_f32 v[140:141], v[140:141], v[212:213] op_sel_hi:[1,0]
	v_pk_mul_f32 v[142:143], v[142:143], v[212:213] op_sel_hi:[1,0]
	v_pk_mul_f32 v[140:141], v[44:45], v[140:141]
	v_pk_mul_f32 v[142:143], v[46:47], v[142:143]
	global_store_dwordx4 v[2:3], v[140:143], off offset:3072
	v_pk_mul_f32 v[144:145], v[144:145], v[212:213] op_sel_hi:[1,0]
	v_pk_mul_f32 v[146:147], v[146:147], v[212:213] op_sel_hi:[1,0]
	v_pk_mul_f32 v[144:145], v[48:49], v[144:145]
	v_pk_mul_f32 v[146:147], v[50:51], v[146:147]
	global_store_dwordx4 v[2:3], v[144:147], off offset:3584
	v_lshl_add_u64 v[2:3], v[2:3], 0, s[6:7]
	s_cmp_lt_u32 3, s8
	s_cbranch_scc0 .Lp8b_done
; __device__ __forceinline__ void rms_row2_f32(float* xrow0, const float* g, int lane, bool second_valid) {
;     ...
;     for (int j = 0; j < 8; ++j) { v[j] = NTL(xr + 32 * j); s += (v[j].x * v[j].x + v[j].y * v[j].y) + (v[j].z * v[j].z + v[j].w * v[j].w); }
; #pragma unroll
;     for (int o = 1; o < 32; o <<= 1) s += __shfl_xor(s, o);
;     const float rstd = 1.f / sqrtf(s * (1.f / DM) + EPS);
; #pragma unroll
;     for (int j = 0; j < 8; ++j) { const f32x4 gg = gr[32 * j]; xr[32 * j] = v[j] * rstd * gg; }
	s_waitcnt vmcnt(24)
	v_mov_b32_e32 v214, v149
	v_mov_b32_e32 v215, v153
	v_mov_b32_e32 v218, v151
	v_mov_b32_e32 v219, v155
	v_mov_b32_e32 v212, v148
	v_mov_b32_e32 v213, v152
	v_mov_b32_e32 v216, v150
	v_mov_b32_e32 v217, v154
	v_pk_mul_f32 v[220:221], v[158:159], v[158:159]
	v_pk_mul_f32 v[222:223], v[156:157], v[156:157]
	v_pk_mul_f32 v[214:215], v[214:215], v[214:215]
	v_pk_mul_f32 v[218:219], v[218:219], v[218:219]
	v_pk_mov_b32 v[236:237], v[222:223], v[220:221] op_sel:[1,0]
	v_mov_b32_e32 v223, v221
	v_pk_fma_f32 v[212:213], v[212:213], v[212:213], v[214:215]
	v_pk_fma_f32 v[214:215], v[216:217], v[216:217], v[218:219]
	v_mul_f32_e32 v224, v161, v161
	v_mul_f32_e32 v226, v163, v163
	v_pk_add_f32 v[216:217], v[236:237], v[222:223]
	v_pk_add_f32 v[212:213], v[212:213], v[214:215]
	v_mul_f32_e32 v4, v164, v164
	v_mul_f32_e32 v235, v165, v165
	v_mul_f32_e32 v238, v166, v166
	v_mul_f32_e32 v239, v167, v167
	v_pk_fma_f32 v[220:221], v[160:161], v[160:161], v[224:225] op_sel_hi:[1,1,0]
	v_pk_fma_f32 v[224:225], v[162:163], v[162:163], v[226:227] op_sel_hi:[1,1,0]
	v_pk_add_f32 v[214:215], v[216:217], v[216:217] op_sel:[0,1] op_sel_hi:[1,0]
	v_pk_add_f32 v[212:213], v[212:213], v[212:213] op_sel:[0,1] op_sel_hi:[1,0]
	v_pk_mul_f32 v[228:229], v[170:171], v[170:171]
	v_pk_mul_f32 v[230:231], v[168:169], v[168:169]
	v_mov_b32_e32 v221, v238
	v_mov_b32_e32 v225, v239
	v_mov_b32_e32 v215, v235
	v_mov_b32_e32 v213, v4
	v_pk_mov_b32 v[226:227], v[230:231], v[228:229] op_sel:[1,0]
	v_mov_b32_e32 v231, v229
	v_pk_add_f32 v[216:217], v[220:221], v[224:225]
	v_pk_add_f32 v[212:213], v[212:213], v[214:215]
	v_mul_f32_e32 v232, v173, v173
	v_mul_f32_e32 v234, v175, v175
	v_pk_add_f32 v[218:219], v[226:227], v[230:231]
	v_pk_add_f32 v[212:213], v[212:213], v[216:217]
	v_mul_f32_e32 v240, v176, v176
	v_mul_f32_e32 v241, v177, v177
	v_mul_f32_e32 v242, v178, v178
	v_mul_f32_e32 v243, v179, v179
	v_pk_fma_f32 v[228:229], v[172:173], v[172:173], v[232:233] op_sel_hi:[1,1,0]
	v_pk_fma_f32 v[232:233], v[174:175], v[174:175], v[234:235] op_sel_hi:[1,1,0]
	v_pk_add_f32 v[218:219], v[218:219], v[218:219] op_sel:[0,1] op_sel_hi:[1,0]
	v_pk_add_f32 v[212:213], v[212:213], v[212:213] op_sel:[0,1] op_sel_hi:[1,0]
	v_mov_b32_e32 v229, v242
	v_mov_b32_e32 v233, v243
	v_mov_b32_e32 v219, v241
	v_mov_b32_e32 v213, v240
	v_pk_add_f32 v[220:221], v[228:229], v[232:233]
	v_pk_add_f32 v[212:213], v[212:213], v[218:219]
	s_nop 0
	v_pk_add_f32 v[212:213], v[212:213], v[220:221]
	s_nop 0
	v_add_f32_e32 v4, v212, v213
	ds_bpermute_b32 v212, v12, v4
	s_waitcnt lgkmcnt(0)
	v_add_f32_e32 v4, v4, v212
	ds_bpermute_b32 v212, v13, v4
	s_waitcnt lgkmcnt(0)
	v_add_f32_e32 v4, v4, v212
	ds_bpermute_b32 v212, v14, v4
	s_waitcnt lgkmcnt(0)
	v_add_f32_e32 v4, v4, v212
	ds_bpermute_b32 v212, v15, v4
	s_waitcnt lgkmcnt(0)
	v_add_f32_e32 v4, v4, v212
	ds_bpermute_b32 v212, v16, v4
	s_waitcnt lgkmcnt(0)
	v_add_f32_e32 v4, v4, v212
	v_fmamk_f32 v4, v4, 0x3a800000, v17
	v_mul_f32_e32 v212, 0x4f800000, v4
	v_cmp_gt_f32_e32 vcc, s3, v4
	s_nop 1
	v_cndmask_b32_e32 v4, v4, v212, vcc
	v_sqrt_f32_e32 v212, v4
	s_nop 0
	v_add_u32_e32 v213, -1, v212
	v_add_u32_e32 v214, 1, v212
	v_fma_f32 v215, -v213, v212, v4
	v_fma_f32 v216, -v214, v212, v4
	v_cmp_ge_f32_e64 s[0:1], 0, v215
	s_nop 1
	v_cndmask_b32_e64 v212, v212, v213, s[0:1]
	v_cmp_lt_f32_e64 s[0:1], 0, v216
	s_nop 1
	v_cndmask_b32_e64 v212, v212, v214, s[0:1]
	v_mul_f32_e32 v213, 0x37800000, v212
	v_cndmask_b32_e32 v212, v212, v213, vcc
	v_cmp_class_f32_e32 vcc, v4, v18
	s_nop 1
	v_cndmask_b32_e32 v4, v212, v4, vcc
	v_div_scale_f32 v212, s[0:1], v4, v4, 1.0
	v_rcp_f32_e32 v213, v212
	v_div_scale_f32 v214, vcc, 1.0, v4, 1.0
	v_fma_f32 v215, -v212, v213, 1.0
	v_fmac_f32_e32 v213, v215, v213
	v_mul_f32_e32 v215, v214, v213
	v_fma_f32 v216, -v212, v215, v214
	v_fmac_f32_e32 v215, v216, v213
	v_fma_f32 v212, -v212, v215, v214
	v_div_fmas_f32 v212, v212, v213, v215
	v_div_fixup_f32 v212, v212, v4, 1.0
	v_pk_mul_f32 v[148:149], v[148:149], v[212:213] op_sel_hi:[1,0]
	v_pk_mul_f32 v[150:151], v[150:151], v[212:213] op_sel_hi:[1,0]
	v_pk_mul_f32 v[148:149], v[20:21], v[148:149]
	v_pk_mul_f32 v[150:151], v[22:23], v[150:151]
	global_store_dwordx4 v[2:3], v[148:151], off offset:0
	v_pk_mul_f32 v[152:153], v[152:153], v[212:213] op_sel_hi:[1,0]
	v_pk_mul_f32 v[154:155], v[154:155], v[212:213] op_sel_hi:[1,0]
	v_pk_mul_f32 v[152:153], v[24:25], v[152:153]
	v_pk_mul_f32 v[154:155], v[26:27], v[154:155]
	global_store_dwordx4 v[2:3], v[152:155], off offset:512
	v_pk_mul_f32 v[156:157], v[156:157], v[212:213] op_sel_hi:[1,0]
	v_pk_mul_f32 v[158:159], v[158:159], v[212:213] op_sel_hi:[1,0]
	v_pk_mul_f32 v[156:157], v[28:29], v[156:157]
	v_pk_mul_f32 v[158:159], v[30:31], v[158:159]
	global_store_dwordx4 v[2:3], v[156:159], off offset:1024
	v_pk_mul_f32 v[160:161], v[160:161], v[212:213] op_sel_hi:[1,0]
	v_pk_mul_f32 v[162:163], v[162:163], v[212:213] op_sel_hi:[1,0]
	v_pk_mul_f32 v[160:161], v[32:33], v[160:161]
	v_pk_mul_f32 v[162:163], v[34:35], v[162:163]
	global_store_dwordx4 v[2:3], v[160:163], off offset:1536
	v_pk_mul_f32 v[164:165], v[164:165], v[212:213] op_sel_hi:[1,0]
	v_pk_mul_f32 v[166:167], v[166:167], v[212:213] op_sel_hi:[1,0]
	v_pk_mul_f32 v[164:165], v[36:37], v[164:165]
	v_pk_mul_f32 v[166:167], v[38:39], v[166:167]
	global_store_dwordx4 v[2:3], v[164:167], off offset:2048
	v_pk_mul_f32 v[168:169], v[168:169], v[212:213] op_sel_hi:[1,0]
	v_pk_mul_f32 v[170:171], v[170:171], v[212:213] op_sel_hi:[1,0]
	v_pk_mul_f32 v[168:169], v[40:41], v[168:169]
	v_pk_mul_f32 v[170:171], v[42:43], v[170:171]
	global_store_dwordx4 v[2:3], v[168:171], off offset:2560
	v_pk_mul_f32 v[172:173], v[172:173], v[212:213] op_sel_hi:[1,0]
	v_pk_mul_f32 v[174:175], v[174:175], v[212:213] op_sel_hi:[1,0]
	v_pk_mul_f32 v[172:173], v[44:45], v[172:173]
	v_pk_mul_f32 v[174:175], v[46:47], v[174:175]
	global_store_dwordx4 v[2:3], v[172:175], off offset:3072
	v_pk_mul_f32 v[176:177], v[176:177], v[212:213] op_sel_hi:[1,0]
	v_pk_mul_f32 v[178:179], v[178:179], v[212:213] op_sel_hi:[1,0]
	v_pk_mul_f32 v[176:177], v[48:49], v[176:177]
	v_pk_mul_f32 v[178:179], v[50:51], v[178:179]
	global_store_dwordx4 v[2:3], v[176:179], off offset:3584
	v_lshl_add_u64 v[2:3], v[2:3], 0, s[6:7]
	s_cmp_lt_u32 4, s8
	s_cbranch_scc0 .Lp8b_done
; __device__ __forceinline__ void rms_row2_f32(float* xrow0, const float* g, int lane, bool second_valid) {
;     ...
;     for (int j = 0; j < 8; ++j) { v[j] = NTL(xr + 32 * j); s += (v[j].x * v[j].x + v[j].y * v[j].y) + (v[j].z * v[j].z + v[j].w * v[j].w); }
; #pragma unroll
;     for (int o = 1; o < 32; o <<= 1) s += __shfl_xor(s, o);
;     const float rstd = 1.f / sqrtf(s * (1.f / DM) + EPS);
; #pragma unroll
;     for (int j = 0; j < 8; ++j) { const f32x4 gg = gr[32 * j]; xr[32 * j] = v[j] * rstd * gg; }
	s_waitcnt vmcnt(24)
	v_mov_b32_e32 v214, v181
	v_mov_b32_e32 v215, v185
	v_mov_b32_e32 v218, v183
	v_mov_b32_e32 v219, v187
	v_mov_b32_e32 v212, v180
	v_mov_b32_e32 v213, v184
	v_mov_b32_e32 v216, v182
	v_mov_b32_e32 v217, v186
	v_pk_mul_f32 v[220:221], v[190:191], v[190:191]
	v_pk_mul_f32 v[222:223], v[188:189], v[188:189]
	v_pk_mul_f32 v[214:215], v[214:215], v[214:215]
	v_pk_mul_f32 v[218:219], v[218:219], v[218:219]
	v_pk_mov_b32 v[236:237], v[222:223], v[220:221] op_sel:[1,0]
	v_mov_b32_e32 v223, v221
	v_pk_fma_f32 v[212:213], v[212:213], v[212:213], v[214:215]
	v_pk_fma_f32 v[214:215], v[216:217], v[216:217], v[218:219]
	v_mul_f32_e32 v224, v193, v193
	v_mul_f32_e32 v226, v195, v195
	v_pk_add_f32 v[216:217], v[236:237], v[222:223]
	v_pk_add_f32 v[212:213], v[212:213], v[214:215]
	v_mul_f32_e32 v4, v196, v196
	v_mul_f32_e32 v235, v197, v197
	v_mul_f32_e32 v238, v198, v198
	v_mul_f32_e32 v239, v199, v199
	v_pk_fma_f32 v[220:221], v[192:193], v[192:193], v[224:225] op_sel_hi:[1,1,0]
	v_pk_fma_f32 v[224:225], v[194:195], v[194:195], v[226:227] op_sel_hi:[1,1,0]
	v_pk_add_f32 v[214:215], v[216:217], v[216:217] op_sel:[0,1] op_sel_hi:[1,0]
	v_pk_add_f32 v[212:213], v[212:213], v[212:213] op_sel:[0,1] op_sel_hi:[1,0]
	v_pk_mul_f32 v[228:229], v[202:203], v[202:203]
	v_pk_mul_f32 v[230:231], v[200:201], v[200:201]
	v_mov_b32_e32 v221, v238
	v_mov_b32_e32 v225, v239
	v_mov_b32_e32 v215, v235
	v_mov_b32_e32 v213, v4
	v_pk_mov_b32 v[226:227], v[230:231], v[228:229] op_sel:[1,0]
	v_mov_b32_e32 v231, v229
	v_pk_add_f32 v[216:217], v[220:221], v[224:225]
	v_pk_add_f32 v[212:213], v[212:213], v[214:215]
	v_mul_f32_e32 v232, v205, v205
	v_mul_f32_e32 v234, v207, v207
	v_pk_add_f32 v[218:219], v[226:227], v[230:231]
	v_pk_add_f32 v[212:213], v[212:213], v[216:217]
	v_mul_f32_e32 v240, v208, v208
	v_mul_f32_e32 v241, v209, v209
	v_mul_f32_e32 v242, v210, v210
	v_mul_f32_e32 v243, v211, v211
	v_pk_fma_f32 v[228:229], v[204:205], v[204:205], v[232:233] op_sel_hi:[1,1,0]
	v_pk_fma_f32 v[232:233], v[206:207], v[206:207], v[234:235] op_sel_hi:[1,1,0]
	v_pk_add_f32 v[218:219], v[218:219], v[218:219] op_sel:[0,1] op_sel_hi:[1,0]
	v_pk_add_f32 v[212:213], v[212:213], v[212:213] op_sel:[0,1] op_sel_hi:[1,0]
	v_mov_b32_e32 v229, v242
	v_mov_b32_e32 v233, v243
	v_mov_b32_e32 v219, v241
	v_mov_b32_e32 v213, v240
	v_pk_add_f32 v[220:221], v[228:229], v[232:233]
	v_pk_add_f32 v[212:213], v[212:213], v[218:219]
	s_nop 0
	v_pk_add_f32 v[212:213], v[212:213], v[220:221]
	s_nop 0
	v_add_f32_e32 v4, v212, v213
	ds_bpermute_b32 v212, v12, v4
	s_waitcnt lgkmcnt(0)
	v_add_f32_e32 v4, v4, v212
	ds_bpermute_b32 v212, v13, v4
	s_waitcnt lgkmcnt(0)
	v_add_f32_e32 v4, v4, v212
	ds_bpermute_b32 v212, v14, v4
	s_waitcnt lgkmcnt(0)
	v_add_f32_e32 v4, v4, v212
	ds_bpermute_b32 v212, v15, v4
	s_waitcnt lgkmcnt(0)
	v_add_f32_e32 v4, v4, v212
	ds_bpermute_b32 v212, v16, v4
	s_waitcnt lgkmcnt(0)
	v_add_f32_e32 v4, v4, v212
	v_fmamk_f32 v4, v4, 0x3a800000, v17
	v_mul_f32_e32 v212, 0x4f800000, v4
	v_cmp_gt_f32_e32 vcc, s3, v4
	s_nop 1
	v_cndmask_b32_e32 v4, v4, v212, vcc
	v_sqrt_f32_e32 v212, v4
	s_nop 0
	v_add_u32_e32 v213, -1, v212
	v_add_u32_e32 v214, 1, v212
	v_fma_f32 v215, -v213, v212, v4
	v_fma_f32 v216, -v214, v212, v4
	v_cmp_ge_f32_e64 s[0:1], 0, v215
	s_nop 1
	v_cndmask_b32_e64 v212, v212, v213, s[0:1]
	v_cmp_lt_f32_e64 s[0:1], 0, v216
	s_nop 1
	v_cndmask_b32_e64 v212, v212, v214, s[0:1]
	v_mul_f32_e32 v213, 0x37800000, v212
	v_cndmask_b32_e32 v212, v212, v213, vcc
	v_cmp_class_f32_e32 vcc, v4, v18
	s_nop 1
	v_cndmask_b32_e32 v4, v212, v4, vcc
	v_div_scale_f32 v212, s[0:1], v4, v4, 1.0
	v_rcp_f32_e32 v213, v212
	v_div_scale_f32 v214, vcc, 1.0, v4, 1.0
	v_fma_f32 v215, -v212, v213, 1.0
	v_fmac_f32_e32 v213, v215, v213
	v_mul_f32_e32 v215, v214, v213
	v_fma_f32 v216, -v212, v215, v214
	v_fmac_f32_e32 v215, v216, v213
	v_fma_f32 v212, -v212, v215, v214
	v_div_fmas_f32 v212, v212, v213, v215
	v_div_fixup_f32 v212, v212, v4, 1.0
	v_pk_mul_f32 v[180:181], v[180:181], v[212:213] op_sel_hi:[1,0]
	v_pk_mul_f32 v[182:183], v[182:183], v[212:213] op_sel_hi:[1,0]
	v_pk_mul_f32 v[180:181], v[20:21], v[180:181]
	v_pk_mul_f32 v[182:183], v[22:23], v[182:183]
	global_store_dwordx4 v[2:3], v[180:183], off offset:0
	v_pk_mul_f32 v[184:185], v[184:185], v[212:213] op_sel_hi:[1,0]
	v_pk_mul_f32 v[186:187], v[186:187], v[212:213] op_sel_hi:[1,0]
	v_pk_mul_f32 v[184:185], v[24:25], v[184:185]
	v_pk_mul_f32 v[186:187], v[26:27], v[186:187]
	global_store_dwordx4 v[2:3], v[184:187], off offset:512
	v_pk_mul_f32 v[188:189], v[188:189], v[212:213] op_sel_hi:[1,0]
	v_pk_mul_f32 v[190:191], v[190:191], v[212:213] op_sel_hi:[1,0]
	v_pk_mul_f32 v[188:189], v[28:29], v[188:189]
	v_pk_mul_f32 v[190:191], v[30:31], v[190:191]
	global_store_dwordx4 v[2:3], v[188:191], off offset:1024
	v_pk_mul_f32 v[192:193], v[192:193], v[212:213] op_sel_hi:[1,0]
	v_pk_mul_f32 v[194:195], v[194:195], v[212:213] op_sel_hi:[1,0]
	v_pk_mul_f32 v[192:193], v[32:33], v[192:193]
	v_pk_mul_f32 v[194:195], v[34:35], v[194:195]
	global_store_dwordx4 v[2:3], v[192:195], off offset:1536
	v_pk_mul_f32 v[196:197], v[196:197], v[212:213] op_sel_hi:[1,0]
	v_pk_mul_f32 v[198:199], v[198:199], v[212:213] op_sel_hi:[1,0]
	v_pk_mul_f32 v[196:197], v[36:37], v[196:197]
	v_pk_mul_f32 v[198:199], v[38:39], v[198:199]
	global_store_dwordx4 v[2:3], v[196:199], off offset:2048
	v_pk_mul_f32 v[200:201], v[200:201], v[212:213] op_sel_hi:[1,0]
	v_pk_mul_f32 v[202:203], v[202:203], v[212:213] op_sel_hi:[1,0]
	v_pk_mul_f32 v[200:201], v[40:41], v[200:201]
	v_pk_mul_f32 v[202:203], v[42:43], v[202:203]
	global_store_dwordx4 v[2:3], v[200:203], off offset:2560
	v_pk_mul_f32 v[204:205], v[204:205], v[212:213] op_sel_hi:[1,0]
	v_pk_mul_f32 v[206:207], v[206:207], v[212:213] op_sel_hi:[1,0]
	v_pk_mul_f32 v[204:205], v[44:45], v[204:205]
	v_pk_mul_f32 v[206:207], v[46:47], v[206:207]
	global_store_dwordx4 v[2:3], v[204:207], off offset:3072
	v_pk_mul_f32 v[208:209], v[208:209], v[212:213] op_sel_hi:[1,0]
	v_pk_mul_f32 v[210:211], v[210:211], v[212:213] op_sel_hi:[1,0]
	v_pk_mul_f32 v[208:209], v[48:49], v[208:209]
	v_pk_mul_f32 v[210:211], v[50:51], v[210:211]
	global_store_dwordx4 v[2:3], v[208:211], off offset:3584
	v_lshl_add_u64 v[2:3], v[2:3], 0, s[6:7]
.Lp8b_done:
	s_cmpk_lt_i32 s2, 0x4400
	s_cbranch_scc1 .Lp8b_outer

; __global__ void __launch_bounds__(NWAVES * 64, 2) mk_fwd(Args args) {
	.amdhsa_kernel _Z6mk_fwd4Args
		.amdhsa_group_segment_fixed_size 0
		.amdhsa_private_segment_fixed_size 0
		.amdhsa_kernarg_size 448
		.amdhsa_user_sgpr_count 2
		.amdhsa_user_sgpr_dispatch_ptr 0
		.amdhsa_user_sgpr_queue_ptr 0
		.amdhsa_user_sgpr_kernarg_segment_ptr 1
		.amdhsa_user_sgpr_dispatch_id 0
		.amdhsa_user_sgpr_kernarg_preload_length 0
		.amdhsa_user_sgpr_kernarg_preload_offset 0
		.amdhsa_user_sgpr_private_segment_size 0
		.amdhsa_uses_dynamic_stack 0
		.amdhsa_enable_private_segment 0
		.amdhsa_system_sgpr_workgroup_id_x 1
		.amdhsa_system_sgpr_workgroup_id_y 0
		.amdhsa_system_sgpr_workgroup_id_z 0
		.amdhsa_system_sgpr_workgroup_info 0
		.amdhsa_system_vgpr_workitem_id 0
		.amdhsa_next_free_vgpr 244
		.amdhsa_next_free_sgpr 98
		.amdhsa_accum_offset 244
		.amdhsa_reserve_vcc 1
		.amdhsa_float_round_mode_32 0
		.amdhsa_float_round_mode_16_64 0
		.amdhsa_float_denorm_mode_32 3
		.amdhsa_float_denorm_mode_16_64 3
		.amdhsa_dx10_clamp 1
		.amdhsa_ieee_mode 1
		.amdhsa_fp16_overflow 0
		.amdhsa_tg_split 0
		.amdhsa_exception_fp_ieee_invalid_op 0
		.amdhsa_exception_fp_denorm_src 0
		.amdhsa_exception_fp_ieee_div_zero 0
		.amdhsa_exception_fp_ieee_overflow 0
		.amdhsa_exception_fp_ieee_underflow 0
		.amdhsa_exception_fp_ieee_inexact 0
		.amdhsa_exception_int_div_zero 0
	.end_amdhsa_kernel

; __global__ void __launch_bounds__(NWAVES * 64, 2) mk_fwd(Args args) {
amdhsa.kernels:
  - .agpr_count:     0
    .args:
      - .offset:         0
        .size:           192
        .value_kind:     by_value
      - .offset:         192
        .size:           4
        .value_kind:     hidden_block_count_x
      - .offset:         196
        .size:           4
        .value_kind:     hidden_block_count_y
      - .offset:         200
        .size:           4
        .value_kind:     hidden_block_count_z
      - .offset:         204
        .size:           2
        .value_kind:     hidden_group_size_x
      - .offset:         206
        .size:           2
        .value_kind:     hidden_group_size_y
      - .offset:         208
        .size:           2
        .value_kind:     hidden_group_size_z
      - .offset:         210
        .size:           2
        .value_kind:     hidden_remainder_x
      - .offset:         212
        .size:           2
        .value_kind:     hidden_remainder_y
      - .offset:         214
        .size:           2
        .value_kind:     hidden_remainder_z
      - .offset:         232
        .size:           8
        .value_kind:     hidden_global_offset_x
      - .offset:         240
        .size:           8
        .value_kind:     hidden_global_offset_y
      - .offset:         248
        .size:           8
        .value_kind:     hidden_global_offset_z
      - .offset:         256
        .size:           2
        .value_kind:     hidden_grid_dims
      - .offset:         312
        .size:           4
        .value_kind:     hidden_dynamic_lds_size
    .group_segment_fixed_size: 0
    .kernarg_segment_align: 8
    .kernarg_segment_size: 448
    .language:       OpenCL C
    .language_version:
      - 2
      - 0
    .max_flat_workgroup_size: 512
    .name:           _Z6mk_fwd4Args
    .private_segment_fixed_size: 0
    .sgpr_count:     104
    .sgpr_spill_count: 2
    .symbol:         _Z6mk_fwd4Args.kd
    .uniform_work_group_size: 1
    .uses_dynamic_stack: false
    .vgpr_count:     244
    .vgpr_spill_count: 0
    .wavefront_size: 64
